# v59 with the GEMM static priority raise on waves 0-3 instead of waves 4-7 (per-half comparison)
# speedup vs baseline: 1.0065x; 1.0065x over previous
.LBB0_261:
	s_cmp_lt_i32 s92, 3
	s_cselect_b64 s[0:1], -1, 0
	s_waitcnt lgkmcnt(0)
	s_add_u32 s54, s38, 0x596c400
	s_addc_u32 s55, s39, 0
	s_and_b64 s[0:1], s[0:1], s[2:3]
	s_andn2_b64 vcc, exec, s[0:1]
	s_cbranch_vccnz .LBB0_274
	v_mov_b32_e32 v11, v184
	s_cmpk_gt_i32 s33, 0x77f
	v_readfirstlane_b32 s28, v11
	s_cbranch_scc1 .LBB0_274
	v_lshlrev_b32_e32 v1, 4, v11
	v_add_u32_e32 v2, 0x2000, v1
	v_ashrrev_i32_e32 v3, 31, v2
	v_lshrrev_b32_e32 v3, 22, v3
	v_add_u32_e32 v3, v2, v3
	v_ashrrev_i32_e32 v10, 10, v3
	v_mul_i32_i24_e32 v3, 0x400, v10
	v_sub_u32_e32 v2, v2, v3
	v_lshrrev_b32_e32 v3, 4, v2
	v_bitop3_b32 v2, v3, v2, 32 bitop3:0x6c
	v_ashrrev_i32_e32 v3, 31, v2
	v_lshrrev_b32_e32 v3, 26, v3
	v_add_u32_e32 v3, v2, v3
	v_lshlrev_b32_e32 v4, 3, v10
	v_ashrrev_i32_e32 v12, 6, v3
	v_and_b32_e32 v4, -16, v4
	v_add_u32_e32 v4, v12, v4
	v_and_b32_e32 v5, 3, v12
	s_mov_b32 s2, 0xfffe0
	v_lshrrev_b32_e32 v6, 2, v4
	v_lshlrev_b32_e32 v7, 1, v4
	v_and_b32_e32 v3, 0xc0, v3
	v_and_or_b32 v5, v4, s2, v5
	v_and_b32_e32 v6, 4, v6
	v_and_b32_e32 v7, 24, v7
	v_sub_u32_e32 v2, v2, v3
	v_mov_b32_e32 v3, 1
	v_or3_b32 v5, v5, v6, v7
	v_lshlrev_b32_e32 v6, 5, v10
	v_ashrrev_i16_sdwa v2, v3, sext(v2) dst_sel:DWORD dst_unused:UNUSED_PAD src0_sel:DWORD src1_sel:BYTE_0
	v_and_b32_e32 v6, 32, v6
	v_bfe_i32 v13, v2, 0, 16
	v_add_lshl_u32 v2, v6, v13, 1
	v_lshl_add_u32 v130, v5, 12, v2
	v_lshl_add_u32 v132, v4, 12, v2
	v_bfe_i32 v2, v11, 27, 1
	v_lshrrev_b32_e32 v2, 22, v2
	v_add_u32_e32 v2, v1, v2
	v_and_b32_e32 v2, 0xfffffc00, v2
	v_sub_u32_e32 v1, v1, v2
	v_lshrrev_b32_e32 v2, 4, v1
	v_ashrrev_i32_e32 v4, 31, v11
	v_bitop3_b32 v1, v2, v1, 32 bitop3:0x6c
	v_lshrrev_b32_e32 v4, 26, v4
	v_ashrrev_i32_e32 v2, 31, v1
	v_add_u32_e32 v4, v11, v4
	v_lshrrev_b32_e32 v2, 26, v2
	v_ashrrev_i32_e32 v15, 6, v4
	v_add_u32_e32 v2, v1, v2
	v_lshlrev_b32_e32 v4, 3, v15
	v_ashrrev_i32_e32 v14, 6, v2
	v_and_b32_e32 v4, -16, v4
	v_add_u32_e32 v4, v14, v4
	v_and_b32_e32 v5, 3, v14
	s_ashr_i32 s30, s33, 31
	v_and_or_b32 v5, v4, s2, v5
	s_lshr_b32 s2, s30, 29
	s_add_i32 s2, s33, s2
	s_ashr_i32 s4, s28, 6
	s_ashr_i32 s5, s2, 3
	s_and_b32 s2, s2, -8
	s_ashr_i32 s3, s28, 8
	s_lshl_b32 s29, s4, 10
	s_sub_i32 s2, s33, s2
	s_cmp_lt_i32 s2, 0
	s_movk_i32 s31, 0xf1
	s_cselect_b32 s6, s31, 0xf0
	s_mul_i32 s2, s2, s6
	s_add_i32 s2, s2, s5
	s_mul_hi_i32 s5, s2, 0x88888889
	s_add_i32 s5, s5, s2
	s_lshr_b32 s6, s5, 31
	s_ashr_i32 s5, s5, 6
	s_add_i32 s5, s5, s6
	s_lshl_b32 s6, s5, 3
	s_mulk_i32 s5, 0x78
	s_sub_i32 s5, s2, s5
	s_bfe_i32 s2, s5, 0x80000
	s_bfe_u32 s2, s2, 0x3000c
	s_add_i32 s7, s5, s2
	s_bfe_i32 s2, s7, 0x80000
	s_and_b32 s7, s7, 0xf8
	s_sub_i32 s5, s5, s7
	s_sext_i32_i16 s2, s2
	s_sext_i32_i8 s5, s5
	v_lshrrev_b32_e32 v6, 2, v4
	v_lshlrev_b32_e32 v7, 1, v4
	v_and_b32_e32 v2, 0xc0, v2
	s_lshr_b32 s2, s2, 3
	s_add_i32 s20, s6, s5
	v_and_b32_e32 v6, 4, v6
	v_and_b32_e32 v7, 24, v7
	v_sub_u32_e32 v1, v1, v2
	s_ashr_i32 s21, s20, 31
	s_bfe_i64 s[8:9], s[2:3], 0x100000
	v_or3_b32 v5, v5, v6, v7
	v_lshlrev_b32_e32 v6, 5, v15
	v_ashrrev_i16_sdwa v1, v3, sext(v1) dst_sel:DWORD dst_unused:UNUSED_PAD src0_sel:DWORD src1_sel:BYTE_0
	s_lshl_b64 s[6:7], s[20:21], 20
	s_lshl_b64 s[8:9], s[8:9], 20
	v_and_b32_e32 v6, 32, v6
	v_bfe_i32 v16, v1, 0, 16
	s_add_u32 s24, s38, s8
	v_add_lshl_u32 v1, v6, v16, 1
	s_addc_u32 s25, s39, s9
	s_add_i32 s21, s29, 0
	v_lshl_add_u32 v134, v5, 12, v1
	s_add_i32 m0, s21, 0x10000
	v_lshl_add_u32 v136, v4, 12, v1
	global_load_lds_dwordx4 v134, s[24:25]
	s_add_i32 m0, s21, 0x12000
	s_add_u32 s22, s88, s6
	global_load_lds_dwordx4 v130, s[24:25]
	s_addc_u32 s23, s89, s7
	s_mov_b32 m0, s21
	s_add_i32 s34, s21, 0x2000
	global_load_lds_dwordx4 v136, s[22:23]
	s_mov_b32 m0, s34
	s_add_u32 s6, s24, 0x80000
	global_load_lds_dwordx4 v132, s[22:23]
	s_addc_u32 s7, s25, 0
	s_add_i32 m0, s21, 0x14000
	v_mov_b32_e32 v135, 0
	global_load_lds_dwordx4 v134, s[6:7]
	s_add_i32 m0, s21, 0x16000
	v_mov_b32_e32 v131, v135
	global_load_lds_dwordx4 v130, s[6:7]
	s_add_u32 s6, s22, 0x80000
	s_addc_u32 s7, s23, 0
	s_add_i32 s35, s21, 0x4000
	s_mov_b32 m0, s35
	s_add_i32 s36, s21, 0x6000
	global_load_lds_dwordx4 v136, s[6:7]
	s_mov_b32 m0, s36
	v_mov_b32_e32 v137, v135
	global_load_lds_dwordx4 v132, s[6:7]
	v_mov_b32_e32 v133, v135
	s_mov_b32 s37, 0
	v_lshl_add_u64 v[8:9], s[24:25], 0, v[134:135]
	v_lshl_add_u64 v[6:7], s[24:25], 0, v[130:131]
	v_lshl_add_u64 v[4:5], s[22:23], 0, v[136:137]
	s_cmp_lg_u32 s3, 1
	v_lshl_add_u64 v[2:3], s[22:23], 0, v[132:133]
	s_setprio 1
	s_cbranch_scc1 .LBB0_265
	s_setprio 0
	s_barrier

.LBB0_445:
	v_ashrrev_i32_e32 v2, 31, v10
	v_lshrrev_b32_e32 v2, 26, v2
	v_add_u32_e32 v2, v10, v2
	v_ashrrev_i32_e32 v11, 6, v2
	v_bfe_i32 v2, v10, 27, 1
	v_lshlrev_b32_e32 v1, 4, v10
	v_lshrrev_b32_e32 v2, 22, v2
	v_add_u32_e32 v2, v1, v2
	v_and_b32_e32 v2, 0xfffffc00, v2
	v_sub_u32_e32 v2, v1, v2
	v_lshrrev_b32_e32 v3, 4, v2
	v_bitop3_b32 v2, v3, v2, 32 bitop3:0x6c
	v_ashrrev_i32_e32 v4, 31, v2
	v_lshrrev_b32_e32 v4, 26, v4
	v_add_u32_e32 v4, v2, v4
	v_lshlrev_b32_e32 v3, 3, v11
	v_ashrrev_i32_e32 v13, 6, v4
	v_and_b32_e32 v4, 0xc0, v4
	v_and_b32_e32 v3, -16, v3
	v_sub_u32_e32 v2, v2, v4
	v_mov_b32_e32 v4, 1
	s_ashr_i32 s2, s4, 3
	v_add_u32_e32 v3, v13, v3
	v_lshlrev_b32_e32 v5, 5, v11
	v_ashrrev_i16_sdwa v2, v4, sext(v2) dst_sel:DWORD dst_unused:UNUSED_PAD src0_sel:DWORD src1_sel:BYTE_0
	s_add_u32 s41, s38, 0x596dc00
	v_and_b32_e32 v12, 32, v5
	v_bfe_i32 v14, v2, 0, 16
	v_lshlrev_b32_e32 v5, 1, v3
	v_lshrrev_b32_e32 v6, 2, v3
	v_and_b32_e32 v7, 3, v13
	s_mov_b32 s5, 0x3fffe0
	s_movk_i32 s3, 0xf00
	s_addc_u32 s42, s39, 0
	v_add_u32_e32 v2, v12, v14
	v_and_b32_e32 v5, 24, v5
	v_and_b32_e32 v6, 4, v6
	v_and_or_b32 v7, v3, s5, v7
	v_mul_lo_u32 v3, v3, s3
	s_add_u32 s43, s38, 0xf00000
	v_or3_b32 v5, v7, v6, v5
	v_add_lshl_u32 v130, v2, v3, 1
	v_lshlrev_b32_e32 v2, 1, v2
	v_add_u32_e32 v1, 0x2000, v1
	s_addc_u32 s44, s39, 0
	v_lshl_add_u32 v132, v5, 10, v2
	v_ashrrev_i32_e32 v2, 31, v1
	s_add_i32 s2, s6, s2
	v_lshrrev_b32_e32 v2, 22, v2
	s_ashr_i32 s6, s2, 31
	v_add_u32_e32 v2, v1, v2
	s_lshr_b32 s6, s6, 26
	v_ashrrev_i32_e32 v15, 10, v2
	s_add_i32 s6, s2, s6
	v_mul_i32_i24_e32 v2, 0x400, v15
	s_ashr_i32 s7, s6, 6
	s_and_b32 s6, s6, 0xffc0
	v_sub_u32_e32 v1, v1, v2
	s_sub_i32 s6, s2, s6
	v_lshrrev_b32_e32 v2, 4, v1
	s_bfe_i32 s2, s6, 0x80000
	v_bitop3_b32 v1, v2, v1, 32 bitop3:0x6c
	s_bfe_u32 s2, s2, 0x3000c
	v_ashrrev_i32_e32 v3, 31, v1
	s_add_i32 s8, s6, s2
	v_lshrrev_b32_e32 v3, 26, v3
	s_bfe_i32 s2, s8, 0x80000
	s_and_b32 s8, s8, 0xf8
	v_lshlrev_b32_e32 v2, 3, v15
	v_add_u32_e32 v3, v1, v3
	s_sext_i32_i16 s2, s2
	s_sub_i32 s6, s6, s8
	v_and_b32_e32 v2, -16, v2
	v_ashrrev_i32_e32 v16, 6, v3
	v_lshlrev_b32_e32 v5, 5, v15
	s_lshl_b32 s7, s7, 3
	s_lshr_b32 s2, s2, 3
	s_sext_i32_i8 s6, s6
	s_ashr_i32 s4, s36, 6
	v_add_u32_e32 v2, v16, v2
	v_and_b32_e32 v17, 32, v5
	v_and_b32_e32 v3, 0xc0, v3
	v_and_b32_e32 v5, 3, v16
	s_add_i32 s69, s7, s6
	s_bfe_i64 s[6:7], s[2:3], 0x100000
	v_sub_u32_e32 v1, v1, v3
	v_and_or_b32 v5, v2, s5, v5
	s_ashr_i32 s5, s36, 8
	s_lshl_b32 s45, s4, 10
	s_lshl_b64 s[6:7], s[6:7], 18
	v_ashrrev_i16_sdwa v1, v4, sext(v1) dst_sel:DWORD dst_unused:UNUSED_PAD src0_sel:DWORD src1_sel:BYTE_0
	s_add_u32 s30, s43, s6
	v_bfe_i32 v18, v1, 0, 16
	v_lshlrev_b32_e32 v3, 1, v2
	v_lshrrev_b32_e32 v4, 2, v2
	s_addc_u32 s31, s44, s7
	s_add_i32 s46, s45, 0
	v_add_u32_e32 v1, v17, v18
	v_and_b32_e32 v3, 24, v3
	v_and_b32_e32 v4, 4, v4
	v_mul_lo_u32 v2, v2, s3
	s_add_i32 m0, s46, 0x10000
	v_or3_b32 v3, v5, v4, v3
	v_add_lshl_u32 v134, v1, v2, 1
	v_lshlrev_b32_e32 v1, 1, v1
	s_mul_i32 s9, s69, 0x1e0000
	global_load_lds_dwordx4 v132, s[30:31]
	s_add_i32 m0, s46, 0x12000
	v_lshl_add_u32 v136, v3, 10, v1
	s_mul_hi_i32 s8, s69, 0x1e0000
	s_add_u32 s28, s41, s9
	global_load_lds_dwordx4 v136, s[30:31]
	s_addc_u32 s29, s42, s8
	s_mov_b32 m0, s46
	s_add_i32 s47, s46, 0x2000
	global_load_lds_dwordx4 v130, s[28:29]
	s_mov_b32 m0, s47
	s_add_u32 s6, s30, 0x20000
	global_load_lds_dwordx4 v134, s[28:29]
	s_addc_u32 s7, s31, 0
	s_add_i32 m0, s46, 0x14000
	v_mov_b32_e32 v133, 0
	global_load_lds_dwordx4 v132, s[6:7]
	s_add_i32 m0, s46, 0x16000
	v_mov_b32_e32 v137, v133
	global_load_lds_dwordx4 v136, s[6:7]
	s_add_u32 s6, s28, 0xf0000
	s_addc_u32 s7, s29, 0
	s_add_i32 s50, s46, 0x4000
	s_mov_b32 m0, s50
	s_add_i32 s51, s46, 0x6000
	global_load_lds_dwordx4 v130, s[6:7]
	s_mov_b32 m0, s51
	v_mov_b32_e32 v131, v133
	global_load_lds_dwordx4 v134, s[6:7]
	v_mov_b32_e32 v135, v133
	s_mov_b32 s52, 0
	v_lshl_add_u64 v[8:9], s[30:31], 0, v[132:133]
	v_lshl_add_u64 v[6:7], s[30:31], 0, v[136:137]
	v_lshl_add_u64 v[4:5], s[28:29], 0, v[130:131]
	s_cmp_lg_u32 s5, 1
	v_lshl_add_u64 v[2:3], s[28:29], 0, v[134:135]
	s_setprio 1
	s_cbranch_scc1 .LBB0_447
	s_setprio 0
	s_barrier

.LBB0_682:
	v_readlane_b32 s2, v253, 12
	v_readlane_b32 s3, v253, 13
	s_and_b64 vcc, exec, s[2:3]
	s_cbranch_vccnz .LBB0_716
	v_ashrrev_i32_e32 v2, 31, v10
	v_lshrrev_b32_e32 v2, 26, v2
	v_add_u32_e32 v2, v10, v2
	v_ashrrev_i32_e32 v11, 6, v2
	v_bfe_i32 v2, v10, 27, 1
	v_lshlrev_b32_e32 v1, 4, v10
	v_lshrrev_b32_e32 v2, 22, v2
	v_add_u32_e32 v2, v1, v2
	v_and_b32_e32 v2, 0xfffffc00, v2
	v_sub_u32_e32 v2, v1, v2
	v_lshrrev_b32_e32 v3, 4, v2
	v_bitop3_b32 v2, v3, v2, 32 bitop3:0x6c
	v_ashrrev_i32_e32 v4, 31, v2
	v_lshrrev_b32_e32 v4, 26, v4
	v_add_u32_e32 v4, v2, v4
	v_ashrrev_i32_e32 v13, 6, v4
	v_and_b32_e32 v4, 0xc0, v4
	v_lshlrev_b32_e32 v3, 3, v11
	v_sub_u32_e32 v2, v2, v4
	v_mov_b32_e32 v4, 1
	v_and_b32_e32 v3, -16, v3
	v_lshlrev_b32_e32 v5, 5, v11
	v_ashrrev_i16_sdwa v2, v4, sext(v2) dst_sel:DWORD dst_unused:UNUSED_PAD src0_sel:DWORD src1_sel:BYTE_0
	v_add_u32_e32 v3, v13, v3
	v_and_b32_e32 v12, 32, v5
	v_bfe_i32 v14, v2, 0, 16
	s_movk_i32 s6, 0xf00
	v_add_u32_e32 v2, v12, v14
	v_mul_lo_u32 v5, v3, s6
	v_lshlrev_b32_e32 v3, 12, v3
	v_add_u32_e32 v1, 0x2000, v1
	v_add_lshl_u32 v162, v2, v5, 1
	v_lshl_add_u32 v164, v2, 1, v3
	v_ashrrev_i32_e32 v2, 31, v1
	v_lshrrev_b32_e32 v2, 22, v2
	v_add_u32_e32 v2, v1, v2
	v_ashrrev_i32_e32 v15, 10, v2
	v_mul_i32_i24_e32 v2, 0x400, v15
	v_sub_u32_e32 v1, v1, v2
	v_lshrrev_b32_e32 v2, 4, v1
	v_bitop3_b32 v1, v2, v1, 32 bitop3:0x6c
	v_ashrrev_i32_e32 v3, 31, v1
	s_add_u32 s35, s38, 0x1100000
	v_lshrrev_b32_e32 v3, 26, v3
	s_addc_u32 s36, s39, 0
	v_add_u32_e32 v3, v1, v3
	s_ashr_i32 s5, s34, 6
	s_ashr_i32 s1, s0, 31
	s_ashr_i32 s4, s34, 8
	v_ashrrev_i32_e32 v16, 6, v3
	v_and_b32_e32 v3, 0xc0, v3
	s_lshl_b32 s37, s5, 10
	s_lshl_b64 s[2:3], s[0:1], 20
	v_lshlrev_b32_e32 v2, 3, v15
	v_sub_u32_e32 v1, v1, v3
	s_add_u32 s28, s35, s2
	v_and_b32_e32 v2, -16, v2
	v_lshlrev_b32_e32 v5, 5, v15
	v_ashrrev_i16_sdwa v1, v4, sext(v1) dst_sel:DWORD dst_unused:UNUSED_PAD src0_sel:DWORD src1_sel:BYTE_0
	s_addc_u32 s29, s36, s3
	s_add_i32 s41, s37, 0
	v_add_u32_e32 v2, v16, v2
	v_and_b32_e32 v17, 32, v5
	v_bfe_i32 v18, v1, 0, 16
	s_add_i32 m0, s41, 0x10000
	v_add_u32_e32 v1, v17, v18
	v_mul_lo_u32 v3, v2, s6
	v_lshlrev_b32_e32 v2, 12, v2
	s_mul_i32 s8, s52, 0x1e0000
	global_load_lds_dwordx4 v164, s[28:29]
	s_add_i32 m0, s41, 0x12000
	v_lshl_add_u32 v168, v1, 1, v2
	s_mul_hi_i32 s7, s52, 0x1e0000
	s_add_u32 s2, s54, s8
	global_load_lds_dwordx4 v168, s[28:29]
	s_addc_u32 s3, s55, s7
	s_mov_b32 m0, s41
	s_add_i32 s42, s41, 0x2000
	v_add_lshl_u32 v166, v1, v3, 1
	global_load_lds_dwordx4 v162, s[2:3]
	s_mov_b32 m0, s42
	s_add_u32 s8, s28, 0x80000
	global_load_lds_dwordx4 v166, s[2:3]
	s_addc_u32 s9, s29, 0
	s_add_i32 m0, s41, 0x14000
	v_mov_b32_e32 v165, 0
	global_load_lds_dwordx4 v164, s[8:9]
	s_add_i32 m0, s41, 0x16000
	v_mov_b32_e32 v169, v165
	global_load_lds_dwordx4 v168, s[8:9]
	s_add_u32 s8, s2, 0xf0000
	s_addc_u32 s9, s3, 0
	s_add_i32 s43, s41, 0x4000
	s_mov_b32 m0, s43
	s_add_i32 s44, s41, 0x6000
	global_load_lds_dwordx4 v162, s[8:9]
	s_mov_b32 m0, s44
	v_mov_b32_e32 v163, v165
	global_load_lds_dwordx4 v166, s[8:9]
	v_mov_b32_e32 v167, v165
	s_mov_b32 s45, 0
	v_lshl_add_u64 v[8:9], s[28:29], 0, v[164:165]
	v_lshl_add_u64 v[6:7], s[28:29], 0, v[168:169]
	v_lshl_add_u64 v[4:5], s[2:3], 0, v[162:163]
	v_lshl_add_u64 v[2:3], s[2:3], 0, v[166:167]
	s_cmp_lg_u32 s4, 1
	s_movk_i32 s46, 0x4000
	s_setprio 1
	s_cbranch_scc1 .LBB0_685
	s_setprio 0
	s_barrier

.LBB0_791:
	s_andn2_b64 vcc, exec, s[2:3]
	s_cbranch_vccnz .LBB0_875
	v_readlane_b32 s2, v253, 12
	v_mov_b32_e32 v6, v184
	v_readlane_b32 s3, v253, 13
	s_and_b64 vcc, exec, s[2:3]
	v_readfirstlane_b32 s22, v6
	s_cbranch_vccnz .LBB0_808
	s_waitcnt lgkmcnt(0)
	v_lshlrev_b32_e32 v3, 4, v6
	v_add_u32_e32 v1, 0x2000, v3
	v_ashrrev_i32_e32 v0, 31, v1
	v_lshrrev_b32_e32 v0, 22, v0
	v_add_u32_e32 v0, v1, v0
	v_ashrrev_i32_e32 v0, 10, v0
	v_mul_i32_i24_e32 v2, 0x400, v0
	v_sub_u32_e32 v1, v1, v2
	v_lshrrev_b32_e32 v2, 4, v1
	v_bitop3_b32 v2, v2, v1, 32 bitop3:0x6c
	v_ashrrev_i32_e32 v1, 31, v2
	v_lshrrev_b32_e32 v1, 26, v1
	v_add_u32_e32 v4, v2, v1
	v_lshlrev_b32_e32 v5, 3, v0
	v_ashrrev_i32_e32 v1, 6, v4
	v_and_b32_e32 v5, -16, v5
	v_add_u32_e32 v5, v1, v5
	v_and_b32_e32 v7, 3, v1
	s_mov_b32 s4, 0xfffe0
	v_lshrrev_b32_e32 v8, 2, v5
	v_lshlrev_b32_e32 v9, 1, v5
	v_and_b32_e32 v4, 0xc0, v4
	v_and_or_b32 v7, v5, s4, v7
	v_and_b32_e32 v8, 4, v8
	v_and_b32_e32 v9, 24, v9
	v_sub_u32_e32 v2, v2, v4
	v_or3_b32 v7, v7, v8, v9
	v_lshlrev_b32_e32 v8, 5, v0
	v_ashrrev_i16_sdwa v2, v230, sext(v2) dst_sel:DWORD dst_unused:UNUSED_PAD src0_sel:DWORD src1_sel:BYTE_0
	v_and_b32_e32 v8, 32, v8
	v_bfe_i32 v2, v2, 0, 16
	v_add_lshl_u32 v4, v8, v2, 1
	v_lshl_add_u32 v144, v7, 12, v4
	v_lshl_add_u32 v146, v5, 12, v4
	v_bfe_i32 v4, v6, 27, 1
	v_lshrrev_b32_e32 v4, 22, v4
	v_add_u32_e32 v4, v3, v4
	v_and_b32_e32 v4, 0xfffffc00, v4
	v_sub_u32_e32 v3, v3, v4
	v_lshrrev_b32_e32 v4, 4, v3
	v_bitop3_b32 v5, v4, v3, 32 bitop3:0x6c
	v_ashrrev_i32_e32 v4, 31, v6
	v_lshrrev_b32_e32 v4, 26, v4
	v_ashrrev_i32_e32 v3, 31, v5
	v_add_u32_e32 v4, v6, v4
	v_lshrrev_b32_e32 v3, 26, v3
	v_ashrrev_i32_e32 v4, 6, v4
	v_add_u32_e32 v7, v5, v3
	v_lshlrev_b32_e32 v8, 3, v4
	v_ashrrev_i32_e32 v3, 6, v7
	v_and_b32_e32 v8, -16, v8
	v_add_u32_e32 v8, v3, v8
	s_lshl_b32 s2, s47, 25
	v_readlane_b32 s12, v253, 10
	v_and_b32_e32 v9, 3, v3
	v_lshrrev_b32_e32 v10, 2, v8
	v_lshlrev_b32_e32 v11, 1, v8
	v_and_b32_e32 v7, 0xc0, v7
	v_readlane_b32 s13, v253, 11
	s_add_u32 s23, s12, s2
	v_and_or_b32 v9, v8, s4, v9
	v_and_b32_e32 v10, 4, v10
	v_and_b32_e32 v11, 24, v11
	v_sub_u32_e32 v5, v5, v7
	s_addc_u32 s26, s13, 0
	s_ashr_i32 s2, s22, 6
	v_or3_b32 v9, v9, v10, v11
	v_lshlrev_b32_e32 v10, 5, v4
	v_ashrrev_i16_sdwa v5, v230, sext(v5) dst_sel:DWORD dst_unused:UNUSED_PAD src0_sel:DWORD src1_sel:BYTE_0
	s_lshl_b32 s27, s2, 10
	v_and_b32_e32 v10, 32, v10
	v_bfe_i32 v5, v5, 0, 16
	v_add_lshl_u32 v7, v10, v5, 1
	s_add_i32 s16, s27, 0
	v_readlane_b32 s12, v252, 16
	v_lshl_add_u32 v186, v9, 12, v7
	s_add_i32 m0, s16, 0x10000
	v_readlane_b32 s13, v252, 17
	s_ashr_i32 s3, s22, 8
	v_lshl_add_u32 v148, v8, 12, v7
	v_readlane_b32 s14, v252, 14
	v_readlane_b32 s15, v252, 15
	s_nop 0
	global_load_lds_dwordx4 v186, s[12:13]
	s_add_i32 m0, s16, 0x12000
	s_nop 0
	global_load_lds_dwordx4 v144, s[12:13]
	v_readlane_b32 s12, v252, 12
	v_readlane_b32 s13, v252, 13
	s_add_u32 s12, s23, s12
	s_addc_u32 s13, s26, s13
	s_mov_b32 m0, s16
	s_add_i32 s17, s16, 0x2000
	s_nop 0
	global_load_lds_dwordx4 v148, s[12:13]
	s_mov_b32 m0, s17
	s_nop 0
	global_load_lds_dwordx4 v146, s[12:13]
	s_add_i32 m0, s16, 0x14000
	s_nop 0
	global_load_lds_dwordx4 v186, s[14:15]
	s_add_i32 m0, s16, 0x16000
	s_nop 0
	global_load_lds_dwordx4 v144, s[14:15]
	s_add_u32 s14, s12, 0x80000
	s_addc_u32 s15, s13, 0
	s_add_i32 s30, s16, 0x4000
	s_mov_b32 m0, s30
	s_add_i32 s31, s16, 0x6000
	global_load_lds_dwordx4 v148, s[14:15]
	s_mov_b32 m0, s31
	s_cmp_lg_u32 s3, 1
	global_load_lds_dwordx4 v146, s[14:15]
	s_setprio 1
	s_cbranch_scc1 .LBB0_795
	s_setprio 0
	s_barrier

.LBB0_875:
	v_readlane_b32 s12, v253, 6
	v_readlane_b32 s13, v253, 7
	v_readlane_b32 s14, v253, 8
	v_readlane_b32 s15, v253, 9
	s_cmp_le_i32 s12, s16
	s_cselect_b64 s[14:15], -1, 0
	s_cmp_lt_i32 s16, s13
	s_cselect_b64 s[40:41], -1, 0
	s_and_b64 s[2:3], s[14:15], s[40:41]
	s_andn2_b64 vcc, exec, s[2:3]
	s_cbranch_vccnz .LBB0_1019
	v_readlane_b32 s12, v253, 63
	v_readlane_b32 s13, v252, 0
	s_lshl_b32 s35, s47, 13
	s_mov_b64 s[2:3], -1
	v_cndmask_b32_e64 v0, 0, 1, s[12:13]
	s_and_b64 vcc, exec, s[30:31]
	v_cmp_ne_u32_e64 s[42:43], 1, v0
	s_cbranch_vccz .LBB0_926
	v_mov_b32_e32 v6, v184
	s_and_b64 vcc, exec, s[42:43]
	v_readfirstlane_b32 s26, v6
	s_cbranch_vccnz .LBB0_925
	v_lshlrev_b32_e32 v4, 4, v6
	v_add_u32_e32 v1, 0x2000, v4
	v_ashrrev_i32_e32 v0, 31, v1
	v_lshrrev_b32_e32 v0, 22, v0
	v_add_u32_e32 v0, v1, v0
	v_ashrrev_i32_e32 v0, 10, v0
	v_lshlrev_b32_e32 v2, 5, v0
	s_waitcnt lgkmcnt(0)
	v_and_b32_e32 v3, 32, v2
	v_mul_i32_i24_e32 v2, 0x400, v0
	v_sub_u32_e32 v1, v1, v2
	v_lshrrev_b32_e32 v2, 4, v1
	v_bitop3_b32 v2, v2, v1, 32 bitop3:0x6c
	v_ashrrev_i32_e32 v1, 31, v2
	v_lshrrev_b32_e32 v1, 26, v1
	v_add_u32_e32 v5, v2, v1
	v_ashrrev_i32_e32 v1, 6, v5
	v_and_b32_e32 v5, 0xc0, v5
	v_sub_u32_e32 v2, v2, v5
	v_ashrrev_i16_sdwa v2, v230, sext(v2) dst_sel:DWORD dst_unused:UNUSED_PAD src0_sel:DWORD src1_sel:BYTE_0
	v_lshlrev_b32_e32 v5, 3, v0
	v_bfe_i32 v2, v2, 0, 16
	v_and_b32_e32 v5, 0x3fff0, v5
	v_add_u32_e32 v3, v3, v2
	v_add_lshl_u32 v5, v1, v5, 14
	v_lshl_add_u32 v144, v3, 1, v5
	v_ashrrev_i32_e32 v3, 31, v6
	v_lshrrev_b32_e32 v3, 26, v3
	v_add_u32_e32 v3, v6, v3
	v_ashrrev_i32_e32 v3, 6, v3
	v_lshlrev_b32_e32 v5, 5, v3
	v_and_b32_e32 v7, 32, v5
	v_bfe_i32 v5, v6, 27, 1
	v_lshrrev_b32_e32 v5, 22, v5
	v_add_u32_e32 v5, v4, v5
	v_and_b32_e32 v5, 0xfffffc00, v5
	v_sub_u32_e32 v4, v4, v5
	v_lshrrev_b32_e32 v5, 4, v4
	v_bitop3_b32 v5, v5, v4, 32 bitop3:0x6c
	v_ashrrev_i32_e32 v4, 31, v5
	v_lshrrev_b32_e32 v4, 26, v4
	v_add_u32_e32 v8, v5, v4
	v_ashrrev_i32_e32 v4, 6, v8
	v_and_b32_e32 v8, 0xc0, v8
	v_sub_u32_e32 v5, v5, v8
	s_ashr_i32 s2, s26, 6
	v_ashrrev_i16_sdwa v5, v230, sext(v5) dst_sel:DWORD dst_unused:UNUSED_PAD src0_sel:DWORD src1_sel:BYTE_0
	v_lshlrev_b32_e32 v8, 3, v3
	s_lshl_b32 s27, s2, 10
	v_bfe_i32 v5, v5, 0, 16
	v_and_b32_e32 v8, 0x3fff0, v8
	v_add_u32_e32 v7, v7, v5
	v_add_lshl_u32 v8, v4, v8, 14
	s_add_i32 s22, s27, 0
	v_readlane_b32 s12, v252, 29
	v_lshl_add_u32 v146, v7, 1, v8
	s_add_i32 m0, s22, 0x10000
	v_readlane_b32 s13, v252, 30
	s_add_i32 s23, s22, 0x2000
	s_add_i32 s30, s22, 0x4000
	s_add_i32 s31, s22, 0x6000
	s_ashr_i32 s3, s26, 8
	s_nop 0
	global_load_lds_dwordx4 v146, s[12:13]
	s_add_i32 m0, s22, 0x12000
	s_nop 0
	global_load_lds_dwordx4 v144, s[12:13]
	v_readlane_b32 s12, v252, 25
	s_mov_b32 m0, s22
	v_readlane_b32 s13, v252, 26
	s_nop 4
	global_load_lds_dwordx4 v146, s[12:13]
	s_mov_b32 m0, s23
	s_nop 0
	global_load_lds_dwordx4 v144, s[12:13]
	v_readlane_b32 s12, v252, 23
	s_add_i32 m0, s22, 0x14000
	v_readlane_b32 s13, v252, 24
	s_nop 4
	global_load_lds_dwordx4 v146, s[12:13]
	s_add_i32 m0, s22, 0x16000
	s_cmp_lg_u32 s3, 1
	global_load_lds_dwordx4 v144, s[12:13]
	v_readlane_b32 s12, v252, 27
	s_mov_b32 m0, s30
	v_readlane_b32 s13, v252, 28
	s_nop 4
	global_load_lds_dwordx4 v146, s[12:13]
	s_mov_b32 m0, s31
	s_nop 0
	global_load_lds_dwordx4 v144, s[12:13]
	s_setprio 1
	s_cbranch_scc1 .LBB0_880
	s_setprio 0
	s_barrier

.LBB0_926:
	s_andn2_b64 vcc, exec, s[2:3]
	s_cbranch_vccnz .LBB0_1018
	v_mov_b32_e32 v1, v184
	s_and_b64 vcc, exec, s[42:43]
	v_readfirstlane_b32 s16, v1
	s_cbranch_vccnz .LBB0_1018
	v_lshlrev_b32_e32 v5, 4, v1
	v_add_u32_e32 v2, 0x2000, v5
	v_ashrrev_i32_e32 v0, 31, v2
	v_lshrrev_b32_e32 v0, 22, v0
	v_add_u32_e32 v0, v2, v0
	v_ashrrev_i32_e32 v0, 10, v0
	s_waitcnt lgkmcnt(0)
	v_lshlrev_b32_e32 v3, 5, v0
	v_and_b32_e32 v4, 32, v3
	v_mul_i32_i24_e32 v3, 0x400, v0
	v_sub_u32_e32 v2, v2, v3
	v_lshrrev_b32_e32 v3, 4, v2
	v_bitop3_b32 v3, v3, v2, 32 bitop3:0x6c
	v_ashrrev_i32_e32 v2, 31, v3
	v_lshrrev_b32_e32 v2, 26, v2
	v_add_u32_e32 v6, v3, v2
	v_ashrrev_i32_e32 v2, 6, v6
	v_and_b32_e32 v6, 0xc0, v6
	v_sub_u32_e32 v3, v3, v6
	v_ashrrev_i16_sdwa v3, v230, sext(v3) dst_sel:DWORD dst_unused:UNUSED_PAD src0_sel:DWORD src1_sel:BYTE_0
	v_lshlrev_b32_e32 v6, 3, v0
	v_bfe_i32 v3, v3, 0, 16
	v_and_b32_e32 v6, 0x3fff0, v6
	v_add_u32_e32 v4, v4, v3
	v_add_lshl_u32 v6, v2, v6, 14
	v_lshl_add_u32 v128, v4, 1, v6
	v_ashrrev_i32_e32 v4, 31, v1
	v_lshrrev_b32_e32 v4, 26, v4
	v_add_u32_e32 v4, v1, v4
	v_ashrrev_i32_e32 v4, 6, v4
	v_lshlrev_b32_e32 v6, 5, v4
	v_and_b32_e32 v7, 32, v6
	v_bfe_i32 v6, v1, 27, 1
	v_lshrrev_b32_e32 v6, 22, v6
	v_add_u32_e32 v6, v5, v6
	v_and_b32_e32 v6, 0xfffffc00, v6
	v_sub_u32_e32 v5, v5, v6
	v_lshrrev_b32_e32 v6, 4, v5
	v_bitop3_b32 v6, v6, v5, 32 bitop3:0x6c
	v_ashrrev_i32_e32 v5, 31, v6
	v_lshrrev_b32_e32 v5, 26, v5
	v_add_u32_e32 v8, v6, v5
	v_ashrrev_i32_e32 v5, 6, v8
	v_and_b32_e32 v8, 0xc0, v8
	v_sub_u32_e32 v6, v6, v8
	s_ashr_i32 s2, s16, 6
	v_ashrrev_i16_sdwa v6, v230, sext(v6) dst_sel:DWORD dst_unused:UNUSED_PAD src0_sel:DWORD src1_sel:BYTE_0
	v_lshlrev_b32_e32 v8, 3, v4
	s_lshl_b32 s17, s2, 10
	v_bfe_i32 v6, v6, 0, 16
	v_and_b32_e32 v8, 0x3fff0, v8
	v_add_u32_e32 v7, v7, v6
	v_add_lshl_u32 v8, v5, v8, 14
	s_add_i32 s23, s17, 0
	v_readlane_b32 s12, v252, 29
	v_lshl_add_u32 v186, v7, 1, v8
	s_add_i32 m0, s23, 0x10000
	v_readlane_b32 s13, v252, 30
	s_add_i32 s30, s23, 0x2000
	s_add_i32 s31, s23, 0x4000
	s_add_i32 s52, s23, 0x6000
	s_ashr_i32 s3, s16, 8
	s_nop 0
	global_load_lds_dwordx4 v186, s[12:13]
	s_add_i32 m0, s23, 0x12000
	s_nop 0
	global_load_lds_dwordx4 v128, s[12:13]
	v_readlane_b32 s12, v252, 25
	s_mov_b32 m0, s23
	v_readlane_b32 s13, v252, 26
	s_nop 4
	global_load_lds_dwordx4 v186, s[12:13]
	s_mov_b32 m0, s30
	s_nop 0
	global_load_lds_dwordx4 v128, s[12:13]
	v_readlane_b32 s12, v252, 23
	s_add_i32 m0, s23, 0x14000
	v_readlane_b32 s13, v252, 24
	s_nop 4
	global_load_lds_dwordx4 v186, s[12:13]
	s_add_i32 m0, s23, 0x16000
	s_cmp_lg_u32 s3, 1
	global_load_lds_dwordx4 v128, s[12:13]
	v_readlane_b32 s12, v252, 27
	s_mov_b32 m0, s31
	v_readlane_b32 s13, v252, 28
	s_nop 4
	global_load_lds_dwordx4 v186, s[12:13]
	s_mov_b32 m0, s52
	s_nop 0
	global_load_lds_dwordx4 v128, s[12:13]
	s_setprio 1
	s_cbranch_scc1 .LBB0_930
	s_setprio 0
	s_barrier
